# grid barrier: non-leaders poll the cross-XCC release word directly (no per-XCC forwarding hop), on top of the current best
# speedup vs baseline: 1.0036x; 1.0036x over previous
; __device__ __forceinline__ unsigned xb_ld(unsigned* p)              { return __hip_atomic_load(p, __ATOMIC_RELAXED, __HIP_MEMORY_SCOPE_AGENT); }
; __device__ __forceinline__ unsigned xb_add(unsigned* p, unsigned v) { return __hip_atomic_fetch_add(p, v, __ATOMIC_RELAXED, __HIP_MEMORY_SCOPE_AGENT); }
; #define XB_SPIN(cond, bar) do { unsigned _sp = 0; while (cond) { __builtin_amdgcn_s_sleep(1); \
;     if ((++_sp & 255u) == 0u) { if (xb_ld(&(bar)[XB_TMO])) break; if (_sp > XB_SPIN_CAP) { atomicAdd(&(bar)[XB_TMO], 1u); break; } } } } while (0)
; __device__ __forceinline__ void xcd_barrier(const XcdBarrier& b) {
;     ...
;         const unsigned old = xb_add(&bar[XB_XSUB(b.x)], 1u);
;         const unsigned gen = old / nloc;
;         if (old + 1u == (gen + 1u) * nloc) {
;             __builtin_amdgcn_fence(__ATOMIC_RELEASE, "agent");
;             asm volatile("s_waitcnt vmcnt(0)" ::: "memory");
;             const unsigned og = xb_add(&bar[XB_TOP], 1u);
;             const unsigned tg = og / nx;
;             if (og + 1u == (tg + 1u) * nx) xb_add(&bar[XB_TOPGEN], 1u);
;             else XB_SPIN(xb_ld(&bar[XB_TOPGEN]) == tg, bar);
;             __builtin_amdgcn_fence(__ATOMIC_ACQUIRE, "agent");
;             xb_add(&bar[XB_XGEN(b.x)], 1u);
;             asm volatile("s_waitcnt vmcnt(0)" ::: "memory");
;         } else {
;             XB_SPIN(xb_ld(&bar[XB_XGEN(b.x)]) == gen, bar);
;             __builtin_amdgcn_fence(__ATOMIC_ACQUIRE, "agent");
;             asm volatile("s_waitcnt vmcnt(0)" ::: "memory");
;         }
.LBB0_111:
	s_or_b64 exec, exec, s[12:13]
	v_cvt_f32_u32_e32 v5, v3
	s_waitcnt vmcnt(0)
	v_readfirstlane_b32 s10, v4
	v_sub_u32_e32 v4, 0, v3
	v_rcp_iflag_f32_e32 v5, v5
	v_add_u32_e32 v6, s10, v2
	v_mul_f32_e32 v5, 0x4f7ffffe, v5
	v_cvt_u32_f32_e32 v5, v5
	v_mul_lo_u32 v2, v4, v5
	v_mul_hi_u32 v2, v5, v2
	v_add_u32_e32 v2, v5, v2
	v_mul_hi_u32 v2, v6, v2
	v_mul_lo_u32 v4, v2, v3
	v_sub_u32_e32 v4, v6, v4
	v_add_u32_e32 v5, 1, v2
	v_cmp_ge_u32_e32 vcc, v4, v3
	s_nop 1
	v_cndmask_b32_e32 v2, v2, v5, vcc
	v_sub_u32_e32 v5, v4, v3
	v_cndmask_b32_e32 v4, v4, v5, vcc
	v_add_u32_e32 v5, 1, v2
	v_cmp_ge_u32_e32 vcc, v4, v3
	v_add_u32_e32 v4, 1, v6
	s_nop 0
	v_cndmask_b32_e32 v2, v2, v5, vcc
	v_mul_lo_u32 v5, v3, v2
	v_add_u32_e32 v3, v5, v3
	v_cmp_ne_u32_e32 vcc, v4, v3
	s_and_saveexec_b64 s[10:11], vcc
	s_xor_b64 s[10:11], exec, s[10:11]
	s_cbranch_execz .LBB0_125
	s_waitcnt lgkmcnt(0)
	v_mov_b32_e32 v1, 0x83500
	global_load_dword v1, v1, s[80:81] sc1
	s_add_u32 s16, s80, 0x83500
	s_addc_u32 s17, s81, 0
	s_waitcnt vmcnt(0)
	v_cmp_eq_u32_e32 vcc, v1, v2
	s_and_saveexec_b64 s[12:13], vcc
	s_cbranch_execz .LBB0_124
	s_add_u32 s14, s80, 0x80200
	s_addc_u32 s15, s81, 0
	s_mov_b32 s28, 1
	s_mov_b64 s[18:19], 0
	v_mov_b32_e32 v1, 0
	s_branch .LBB0_115

; __device__ __forceinline__ unsigned xb_ld(unsigned* p)              { return __hip_atomic_load(p, __ATOMIC_RELAXED, __HIP_MEMORY_SCOPE_AGENT); }
; __device__ __forceinline__ unsigned xb_add(unsigned* p, unsigned v) { return __hip_atomic_fetch_add(p, v, __ATOMIC_RELAXED, __HIP_MEMORY_SCOPE_AGENT); }
; #define XB_SPIN(cond, bar) do { unsigned _sp = 0; while (cond) { __builtin_amdgcn_s_sleep(1); \
;     if ((++_sp & 255u) == 0u) { if (xb_ld(&(bar)[XB_TMO])) break; if (_sp > XB_SPIN_CAP) { atomicAdd(&(bar)[XB_TMO], 1u); break; } } } } while (0)
; __device__ __forceinline__ void xcd_barrier(const XcdBarrier& b) {
;     ...
;             if (og + 1u == (tg + 1u) * nx) xb_add(&bar[XB_TOPGEN], 1u);
;             else XB_SPIN(xb_ld(&bar[XB_TOPGEN]) == tg, bar);
;             __builtin_amdgcn_fence(__ATOMIC_ACQUIRE, "agent");
;             xb_add(&bar[XB_XGEN(b.x)], 1u);
;             asm volatile("s_waitcnt vmcnt(0)" ::: "memory");
.LBB0_142:
	s_or_b64 exec, exec, s[10:11]
	s_mov_b64 s[10:11], exec
	v_mbcnt_lo_u32_b32 v1, s10, 0
	v_mbcnt_hi_u32_b32 v1, s11, v1
	v_cmp_eq_u32_e32 vcc, 0, v1
	s_waitcnt vmcnt(0)
	buffer_inv sc1
	s_and_saveexec_b64 s[12:13], vcc
	s_cbranch_execz .LBB0_144
	s_bcnt1_i32_b64 s10, s[10:11]
	v_mov_b32_e32 v1, 0x2000
	v_mov_b32_e32 v2, s10
.LBB0_144:
	s_or_b64 exec, exec, s[12:13]
	s_waitcnt vmcnt(0)

; __device__ __forceinline__ unsigned xb_ld(unsigned* p)              { return __hip_atomic_load(p, __ATOMIC_RELAXED, __HIP_MEMORY_SCOPE_AGENT); }
; __device__ __forceinline__ unsigned xb_add(unsigned* p, unsigned v) { return __hip_atomic_fetch_add(p, v, __ATOMIC_RELAXED, __HIP_MEMORY_SCOPE_AGENT); }
; #define XB_SPIN(cond, bar) do { unsigned _sp = 0; while (cond) { __builtin_amdgcn_s_sleep(1); \
;     if ((++_sp & 255u) == 0u) { if (xb_ld(&(bar)[XB_TMO])) break; if (_sp > XB_SPIN_CAP) { atomicAdd(&(bar)[XB_TMO], 1u); break; } } } } while (0)
; __device__ __forceinline__ void xcd_barrier(const XcdBarrier& b) {
;     ...
;             if (og + 1u == (tg + 1u) * nx) xb_add(&bar[XB_TOPGEN], 1u);
;             else XB_SPIN(xb_ld(&bar[XB_TOPGEN]) == tg, bar);
;             __builtin_amdgcn_fence(__ATOMIC_ACQUIRE, "agent");
;             xb_add(&bar[XB_XGEN(b.x)], 1u);
;             asm volatile("s_waitcnt vmcnt(0)" ::: "memory");
.LBB0_383:
	s_or_b64 exec, exec, s[10:11]
	s_mov_b64 s[10:11], exec
	v_mbcnt_lo_u32_b32 v1, s10, 0
	v_mbcnt_hi_u32_b32 v1, s11, v1
	v_cmp_eq_u32_e32 vcc, 0, v1
	s_waitcnt vmcnt(0)
	buffer_inv sc1
	s_and_saveexec_b64 s[12:13], vcc
	s_cbranch_execz .LBB0_385
	s_bcnt1_i32_b64 s10, s[10:11]
	v_mov_b32_e32 v1, 0x2000
	v_mov_b32_e32 v2, s10
.LBB0_385:
	s_or_b64 exec, exec, s[12:13]
	s_waitcnt vmcnt(0)

; __device__ __forceinline__ unsigned xb_ld(unsigned* p)              { return __hip_atomic_load(p, __ATOMIC_RELAXED, __HIP_MEMORY_SCOPE_AGENT); }
; __device__ __forceinline__ unsigned xb_add(unsigned* p, unsigned v) { return __hip_atomic_fetch_add(p, v, __ATOMIC_RELAXED, __HIP_MEMORY_SCOPE_AGENT); }
; #define XB_SPIN(cond, bar) do { unsigned _sp = 0; while (cond) { __builtin_amdgcn_s_sleep(1); \
;     if ((++_sp & 255u) == 0u) { if (xb_ld(&(bar)[XB_TMO])) break; if (_sp > XB_SPIN_CAP) { atomicAdd(&(bar)[XB_TMO], 1u); break; } } } } while (0)
; __device__ __forceinline__ void xcd_barrier(const XcdBarrier& b) {
;     ...
;             if (og + 1u == (tg + 1u) * nx) xb_add(&bar[XB_TOPGEN], 1u);
;             else XB_SPIN(xb_ld(&bar[XB_TOPGEN]) == tg, bar);
;             __builtin_amdgcn_fence(__ATOMIC_ACQUIRE, "agent");
;             xb_add(&bar[XB_XGEN(b.x)], 1u);
;             asm volatile("s_waitcnt vmcnt(0)" ::: "memory");
.LBB0_477:
	s_or_b64 exec, exec, s[10:11]
	s_mov_b64 s[10:11], exec
	v_mbcnt_lo_u32_b32 v1, s10, 0
	v_mbcnt_hi_u32_b32 v1, s11, v1
	v_cmp_eq_u32_e32 vcc, 0, v1
	s_waitcnt vmcnt(0)
	buffer_inv sc1
	s_and_saveexec_b64 s[12:13], vcc
	s_cbranch_execz .LBB0_479
	s_bcnt1_i32_b64 s10, s[10:11]
	v_mov_b32_e32 v1, 0x2000
	v_mov_b32_e32 v2, s10
.LBB0_479:
	s_or_b64 exec, exec, s[12:13]
	s_waitcnt vmcnt(0)

; __device__ __forceinline__ unsigned xb_ld(unsigned* p)              { return __hip_atomic_load(p, __ATOMIC_RELAXED, __HIP_MEMORY_SCOPE_AGENT); }
; __device__ __forceinline__ unsigned xb_add(unsigned* p, unsigned v) { return __hip_atomic_fetch_add(p, v, __ATOMIC_RELAXED, __HIP_MEMORY_SCOPE_AGENT); }
; #define XB_SPIN(cond, bar) do { unsigned _sp = 0; while (cond) { __builtin_amdgcn_s_sleep(1); \
;     if ((++_sp & 255u) == 0u) { if (xb_ld(&(bar)[XB_TMO])) break; if (_sp > XB_SPIN_CAP) { atomicAdd(&(bar)[XB_TMO], 1u); break; } } } } while (0)
; __device__ __forceinline__ void xcd_barrier(const XcdBarrier& b) {
;     ...
;             if (og + 1u == (tg + 1u) * nx) xb_add(&bar[XB_TOPGEN], 1u);
;             else XB_SPIN(xb_ld(&bar[XB_TOPGEN]) == tg, bar);
;             __builtin_amdgcn_fence(__ATOMIC_ACQUIRE, "agent");
;             xb_add(&bar[XB_XGEN(b.x)], 1u);
;             asm volatile("s_waitcnt vmcnt(0)" ::: "memory");
.LBB0_640:
	s_or_b64 exec, exec, s[10:11]
	s_mov_b64 s[10:11], exec
	v_mbcnt_lo_u32_b32 v1, s10, 0
	v_mbcnt_hi_u32_b32 v1, s11, v1
	v_cmp_eq_u32_e32 vcc, 0, v1
	s_waitcnt vmcnt(0)
	buffer_inv sc1
	s_and_saveexec_b64 s[12:13], vcc
	s_cbranch_execz .LBB0_642
	s_bcnt1_i32_b64 s10, s[10:11]
	v_mov_b32_e32 v1, 0x2000
	v_mov_b32_e32 v2, s10
.LBB0_642:
	s_or_b64 exec, exec, s[12:13]
	s_waitcnt vmcnt(0)

; __device__ __forceinline__ unsigned xb_ld(unsigned* p)              { return __hip_atomic_load(p, __ATOMIC_RELAXED, __HIP_MEMORY_SCOPE_AGENT); }
; __device__ __forceinline__ unsigned xb_add(unsigned* p, unsigned v) { return __hip_atomic_fetch_add(p, v, __ATOMIC_RELAXED, __HIP_MEMORY_SCOPE_AGENT); }
; #define XB_SPIN(cond, bar) do { unsigned _sp = 0; while (cond) { __builtin_amdgcn_s_sleep(1); \
;     if ((++_sp & 255u) == 0u) { if (xb_ld(&(bar)[XB_TMO])) break; if (_sp > XB_SPIN_CAP) { atomicAdd(&(bar)[XB_TMO], 1u); break; } } } } while (0)
; __device__ __forceinline__ void xcd_barrier(const XcdBarrier& b) {
;     ...
;             if (og + 1u == (tg + 1u) * nx) xb_add(&bar[XB_TOPGEN], 1u);
;             else XB_SPIN(xb_ld(&bar[XB_TOPGEN]) == tg, bar);
;             __builtin_amdgcn_fence(__ATOMIC_ACQUIRE, "agent");
;             xb_add(&bar[XB_XGEN(b.x)], 1u);
;             asm volatile("s_waitcnt vmcnt(0)" ::: "memory");
.LBB0_800:
	s_or_b64 exec, exec, s[10:11]
	s_mov_b64 s[10:11], exec
	v_mbcnt_lo_u32_b32 v1, s10, 0
	v_mbcnt_hi_u32_b32 v1, s11, v1
	v_cmp_eq_u32_e32 vcc, 0, v1
	s_waitcnt vmcnt(0)
	buffer_inv sc1
	s_and_saveexec_b64 s[12:13], vcc
	s_cbranch_execz .LBB0_802
	s_bcnt1_i32_b64 s10, s[10:11]
	v_mov_b32_e32 v1, 0x2000
	v_mov_b32_e32 v2, s10
.LBB0_802:
	s_or_b64 exec, exec, s[12:13]
	s_waitcnt vmcnt(0)

; __device__ __forceinline__ unsigned xb_ld(unsigned* p)              { return __hip_atomic_load(p, __ATOMIC_RELAXED, __HIP_MEMORY_SCOPE_AGENT); }
; __device__ __forceinline__ unsigned xb_add(unsigned* p, unsigned v) { return __hip_atomic_fetch_add(p, v, __ATOMIC_RELAXED, __HIP_MEMORY_SCOPE_AGENT); }
; #define XB_SPIN(cond, bar) do { unsigned _sp = 0; while (cond) { __builtin_amdgcn_s_sleep(1); \
;     if ((++_sp & 255u) == 0u) { if (xb_ld(&(bar)[XB_TMO])) break; if (_sp > XB_SPIN_CAP) { atomicAdd(&(bar)[XB_TMO], 1u); break; } } } } while (0)
; __device__ __forceinline__ void xcd_barrier(const XcdBarrier& b) {
;     ...
;             if (og + 1u == (tg + 1u) * nx) xb_add(&bar[XB_TOPGEN], 1u);
;             else XB_SPIN(xb_ld(&bar[XB_TOPGEN]) == tg, bar);
;             __builtin_amdgcn_fence(__ATOMIC_ACQUIRE, "agent");
;             xb_add(&bar[XB_XGEN(b.x)], 1u);
;             asm volatile("s_waitcnt vmcnt(0)" ::: "memory");
.LBB0_933:
	s_or_b64 exec, exec, s[10:11]
	s_mov_b64 s[10:11], exec
	v_mbcnt_lo_u32_b32 v1, s10, 0
	v_mbcnt_hi_u32_b32 v1, s11, v1
	v_cmp_eq_u32_e32 vcc, 0, v1
	s_waitcnt vmcnt(0)
	buffer_inv sc1
	s_and_saveexec_b64 s[12:13], vcc
	s_cbranch_execz .LBB0_935
	s_bcnt1_i32_b64 s10, s[10:11]
	v_mov_b32_e32 v1, 0x2000
	v_mov_b32_e32 v2, s10
.LBB0_935:
	s_or_b64 exec, exec, s[12:13]
	s_waitcnt vmcnt(0)

; __device__ __forceinline__ unsigned xb_ld(unsigned* p)              { return __hip_atomic_load(p, __ATOMIC_RELAXED, __HIP_MEMORY_SCOPE_AGENT); }
; __device__ __forceinline__ unsigned xb_add(unsigned* p, unsigned v) { return __hip_atomic_fetch_add(p, v, __ATOMIC_RELAXED, __HIP_MEMORY_SCOPE_AGENT); }
; #define XB_SPIN(cond, bar) do { unsigned _sp = 0; while (cond) { __builtin_amdgcn_s_sleep(1); \
;     if ((++_sp & 255u) == 0u) { if (xb_ld(&(bar)[XB_TMO])) break; if (_sp > XB_SPIN_CAP) { atomicAdd(&(bar)[XB_TMO], 1u); break; } } } } while (0)
; __device__ __forceinline__ void xcd_barrier(const XcdBarrier& b) {
;     ...
;             if (og + 1u == (tg + 1u) * nx) xb_add(&bar[XB_TOPGEN], 1u);
;             else XB_SPIN(xb_ld(&bar[XB_TOPGEN]) == tg, bar);
;             __builtin_amdgcn_fence(__ATOMIC_ACQUIRE, "agent");
;             xb_add(&bar[XB_XGEN(b.x)], 1u);
;             asm volatile("s_waitcnt vmcnt(0)" ::: "memory");
.LBB0_1034:
	s_or_b64 exec, exec, s[10:11]
	s_mov_b64 s[10:11], exec
	v_mbcnt_lo_u32_b32 v1, s10, 0
	v_mbcnt_hi_u32_b32 v1, s11, v1
	v_cmp_eq_u32_e32 vcc, 0, v1
	s_waitcnt vmcnt(0)
	buffer_inv sc1
	s_and_saveexec_b64 s[12:13], vcc
	s_cbranch_execz .LBB0_1036
	s_bcnt1_i32_b64 s10, s[10:11]
	v_mov_b32_e32 v1, 0x2000
	v_mov_b32_e32 v2, s10
.LBB0_1036:
	s_or_b64 exec, exec, s[12:13]
	s_waitcnt vmcnt(0)

; __device__ __forceinline__ unsigned xb_ld(unsigned* p)              { return __hip_atomic_load(p, __ATOMIC_RELAXED, __HIP_MEMORY_SCOPE_AGENT); }
; __device__ __forceinline__ unsigned xb_add(unsigned* p, unsigned v) { return __hip_atomic_fetch_add(p, v, __ATOMIC_RELAXED, __HIP_MEMORY_SCOPE_AGENT); }
; #define XB_SPIN(cond, bar) do { unsigned _sp = 0; while (cond) { __builtin_amdgcn_s_sleep(1); \
;     if ((++_sp & 255u) == 0u) { if (xb_ld(&(bar)[XB_TMO])) break; if (_sp > XB_SPIN_CAP) { atomicAdd(&(bar)[XB_TMO], 1u); break; } } } } while (0)
; __device__ __forceinline__ void xcd_barrier(const XcdBarrier& b) {
;     ...
;             if (og + 1u == (tg + 1u) * nx) xb_add(&bar[XB_TOPGEN], 1u);
;             else XB_SPIN(xb_ld(&bar[XB_TOPGEN]) == tg, bar);
;             __builtin_amdgcn_fence(__ATOMIC_ACQUIRE, "agent");
;             xb_add(&bar[XB_XGEN(b.x)], 1u);
;             asm volatile("s_waitcnt vmcnt(0)" ::: "memory");
.LBB0_1155:
	s_or_b64 exec, exec, s[10:11]
	s_mov_b64 s[10:11], exec
	v_mbcnt_lo_u32_b32 v1, s10, 0
	v_mbcnt_hi_u32_b32 v1, s11, v1
	v_cmp_eq_u32_e32 vcc, 0, v1
	s_waitcnt vmcnt(0)
	buffer_inv sc1
	s_and_saveexec_b64 s[12:13], vcc
	s_cbranch_execz .LBB0_1157
	s_bcnt1_i32_b64 s10, s[10:11]
	v_mov_b32_e32 v1, 0x2000
	v_mov_b32_e32 v2, s10
.LBB0_1157:
	s_or_b64 exec, exec, s[12:13]
	s_waitcnt vmcnt(0)

; __device__ __forceinline__ unsigned xb_ld(unsigned* p)              { return __hip_atomic_load(p, __ATOMIC_RELAXED, __HIP_MEMORY_SCOPE_AGENT); }
; __device__ __forceinline__ unsigned xb_add(unsigned* p, unsigned v) { return __hip_atomic_fetch_add(p, v, __ATOMIC_RELAXED, __HIP_MEMORY_SCOPE_AGENT); }
; #define XB_SPIN(cond, bar) do { unsigned _sp = 0; while (cond) { __builtin_amdgcn_s_sleep(1); \
;     if ((++_sp & 255u) == 0u) { if (xb_ld(&(bar)[XB_TMO])) break; if (_sp > XB_SPIN_CAP) { atomicAdd(&(bar)[XB_TMO], 1u); break; } } } } while (0)
; __device__ __forceinline__ void xcd_barrier(const XcdBarrier& b) {
;     ...
;         const unsigned old = xb_add(&bar[XB_XSUB(b.x)], 1u);
;         const unsigned gen = old / nloc;
;         if (old + 1u == (gen + 1u) * nloc) {
;             __builtin_amdgcn_fence(__ATOMIC_RELEASE, "agent");
;             asm volatile("s_waitcnt vmcnt(0)" ::: "memory");
;             const unsigned og = xb_add(&bar[XB_TOP], 1u);
;             const unsigned tg = og / nx;
;             if (og + 1u == (tg + 1u) * nx) xb_add(&bar[XB_TOPGEN], 1u);
;             else XB_SPIN(xb_ld(&bar[XB_TOPGEN]) == tg, bar);
;             __builtin_amdgcn_fence(__ATOMIC_ACQUIRE, "agent");
;             xb_add(&bar[XB_XGEN(b.x)], 1u);
;             asm volatile("s_waitcnt vmcnt(0)" ::: "memory");
;         } else {
;             XB_SPIN(xb_ld(&bar[XB_XGEN(b.x)]) == gen, bar);
;             __builtin_amdgcn_fence(__ATOMIC_ACQUIRE, "agent");
;             asm volatile("s_waitcnt vmcnt(0)" ::: "memory");
;         }
.LBB0_1254:
	s_or_b64 exec, exec, s[12:13]
	v_cvt_f32_u32_e32 v4, v2
	s_waitcnt vmcnt(0)
	v_readfirstlane_b32 s10, v3
	v_sub_u32_e32 v3, 0, v2
	v_rcp_iflag_f32_e32 v4, v4
	v_add_u32_e32 v5, s10, v1
	v_mul_f32_e32 v4, 0x4f7ffffe, v4
	v_cvt_u32_f32_e32 v4, v4
	v_mul_lo_u32 v1, v3, v4
	v_mul_hi_u32 v1, v4, v1
	v_add_u32_e32 v1, v4, v1
	v_mul_hi_u32 v1, v5, v1
	v_mul_lo_u32 v3, v1, v2
	v_sub_u32_e32 v3, v5, v3
	v_add_u32_e32 v4, 1, v1
	v_cmp_ge_u32_e32 vcc, v3, v2
	s_nop 1
	v_cndmask_b32_e32 v1, v1, v4, vcc
	v_sub_u32_e32 v4, v3, v2
	v_cndmask_b32_e32 v3, v3, v4, vcc
	v_add_u32_e32 v4, 1, v1
	v_cmp_ge_u32_e32 vcc, v3, v2
	v_add_u32_e32 v3, 1, v5
	s_nop 0
	v_cndmask_b32_e32 v1, v1, v4, vcc
	v_mul_lo_u32 v4, v2, v1
	v_add_u32_e32 v2, v4, v2
	v_cmp_ne_u32_e32 vcc, v3, v2
	s_and_saveexec_b64 s[10:11], vcc
	s_xor_b64 s[10:11], exec, s[10:11]
	s_cbranch_execz .LBB0_1268
	s_waitcnt lgkmcnt(0)
	v_mov_b32_e32 v0, 0x83500
	global_load_dword v0, v0, s[80:81] sc1
	s_add_u32 s16, s80, 0x83500
	s_addc_u32 s17, s81, 0
	s_waitcnt vmcnt(0)
	v_cmp_eq_u32_e32 vcc, v0, v1
	s_and_saveexec_b64 s[12:13], vcc
	s_cbranch_execz .LBB0_1267
	s_add_u32 s14, s80, 0x80200
	s_addc_u32 s15, s81, 0
	s_mov_b32 s28, 1
	s_mov_b64 s[18:19], 0
	v_mov_b32_e32 v0, 0
	s_branch .LBB0_1258

; __device__ __forceinline__ unsigned xb_ld(unsigned* p)              { return __hip_atomic_load(p, __ATOMIC_RELAXED, __HIP_MEMORY_SCOPE_AGENT); }
; __device__ __forceinline__ unsigned xb_add(unsigned* p, unsigned v) { return __hip_atomic_fetch_add(p, v, __ATOMIC_RELAXED, __HIP_MEMORY_SCOPE_AGENT); }
; #define XB_SPIN(cond, bar) do { unsigned _sp = 0; while (cond) { __builtin_amdgcn_s_sleep(1); \
;     if ((++_sp & 255u) == 0u) { if (xb_ld(&(bar)[XB_TMO])) break; if (_sp > XB_SPIN_CAP) { atomicAdd(&(bar)[XB_TMO], 1u); break; } } } } while (0)
; __device__ __forceinline__ void xcd_barrier(const XcdBarrier& b) {
;     ...
;             if (og + 1u == (tg + 1u) * nx) xb_add(&bar[XB_TOPGEN], 1u);
;             else XB_SPIN(xb_ld(&bar[XB_TOPGEN]) == tg, bar);
;             __builtin_amdgcn_fence(__ATOMIC_ACQUIRE, "agent");
;             xb_add(&bar[XB_XGEN(b.x)], 1u);
;             asm volatile("s_waitcnt vmcnt(0)" ::: "memory");
.LBB0_1285:
	s_or_b64 exec, exec, s[10:11]
	s_mov_b64 s[10:11], exec
	v_mbcnt_lo_u32_b32 v0, s10, 0
	v_mbcnt_hi_u32_b32 v0, s11, v0
	v_cmp_eq_u32_e32 vcc, 0, v0
	s_waitcnt vmcnt(0)
	buffer_inv sc1
	s_and_saveexec_b64 s[12:13], vcc
	s_cbranch_execz .LBB0_1287
	s_bcnt1_i32_b64 s10, s[10:11]
	v_mov_b32_e32 v0, 0x2000
	v_mov_b32_e32 v1, s10
.LBB0_1287:
	s_or_b64 exec, exec, s[12:13]
	s_waitcnt vmcnt(0)
